# K-loops: removed redundant lgkmcnt(0) after barrier and mid-segment setprio 0/1 flip pair (one prio-1 region per 32-MFMA segment)
# baseline (speedup 1.0000x reference)
.LBB0_453:
	s_add_u32 s24, s22, 0xfffc0080
	s_addc_u32 s25, s23, -1
	s_add_i32 s76, 0, 0x10000
	s_cmp_eq_u32 vcc_lo, 12
	s_cselect_b32 s29, s30, s25
	s_cselect_b32 s28, s31, s24
	v_add_u32_e32 v114, s76, v220
	s_cselect_b32 s25, s69, s99
	s_cselect_b32 s24, s75, s81
	s_add_i32 vcc_hi, 0, 0x14000
	ds_read_b128 v[106:109], v114
	ds_read_b128 v[110:113], v114 offset:1024
	ds_read_b128 v[128:131], v114 offset:2048
	ds_read_b128 v[132:135], v114 offset:3072
	v_add_u32_e32 v114, vcc_hi, v220
	ds_read_b128 v[136:139], v114
	ds_read_b128 v[158:161], v114 offset:1024
	ds_read_b128 v[162:165], v114 offset:2048
	ds_read_b128 v[166:169], v114 offset:3072
	s_add_i32 m0, s57, 0xc000
	ds_read_b128 v[170:173], v234
	ds_read_b128 v[174:177], v234 offset:1024
	ds_read_b128 v[178:181], v234 offset:2048
	ds_read_b128 v[198:201], v234 offset:3072
	ds_read_b128 v[202:205], v234 offset:4096
	ds_read_b128 v[206:209], v234 offset:5120
	ds_read_b128 v[210:213], v234 offset:6144
	ds_read_b128 v[214:217], v234 offset:7168
	global_load_lds_dwordx4 v194, s[22:23]
	s_add_i32 m0, s57, 0xe000
	s_nop 0
	global_load_lds_dwordx4 v196, s[22:23]
	s_waitcnt vmcnt(8)
	s_waitcnt lgkmcnt(0)
	s_barrier
	s_setprio 1
	v_mfma_f32_16x16x32_bf16 v[124:127], v[106:109], v[170:173], v[124:127]
	v_mfma_f32_16x16x32_bf16 v[98:101], v[128:131], v[170:173], v[98:101]
	v_mfma_f32_16x16x32_bf16 v[154:157], v[106:109], v[178:181], v[154:157]
	v_mfma_f32_16x16x32_bf16 v[58:61], v[128:131], v[178:181], v[58:61]
	v_mfma_f32_16x16x32_bf16 v[146:149], v[106:109], v[202:205], v[146:149]
	v_mfma_f32_16x16x32_bf16 v[46:49], v[128:131], v[202:205], v[46:49]
	v_mfma_f32_16x16x32_bf16 v[102:105], v[106:109], v[210:213], v[102:105]
	v_mfma_f32_16x16x32_bf16 v[54:57], v[128:131], v[210:213], v[54:57]
	v_mfma_f32_16x16x32_bf16 v[124:127], v[110:113], v[174:177], v[124:127]
	v_mfma_f32_16x16x32_bf16 v[98:101], v[132:135], v[174:177], v[98:101]
	v_mfma_f32_16x16x32_bf16 v[154:157], v[110:113], v[198:201], v[154:157]
	v_mfma_f32_16x16x32_bf16 v[58:61], v[132:135], v[198:201], v[58:61]
	v_mfma_f32_16x16x32_bf16 v[146:149], v[110:113], v[206:209], v[146:149]
	v_mfma_f32_16x16x32_bf16 v[46:49], v[132:135], v[206:209], v[46:49]
	v_mfma_f32_16x16x32_bf16 v[102:105], v[110:113], v[214:217], v[102:105]
	v_mfma_f32_16x16x32_bf16 v[54:57], v[132:135], v[214:217], v[54:57]
	v_mfma_f32_16x16x32_bf16 v[120:123], v[136:139], v[170:173], v[120:123]
	v_mfma_f32_16x16x32_bf16 v[94:97], v[162:165], v[170:173], v[94:97]
	v_mfma_f32_16x16x32_bf16 v[150:153], v[136:139], v[178:181], v[150:153]
	v_mfma_f32_16x16x32_bf16 v[50:53], v[162:165], v[178:181], v[50:53]
	v_mfma_f32_16x16x32_bf16 v[140:143], v[136:139], v[202:205], v[142:145]
	v_mfma_f32_16x16x32_bf16 v[42:45], v[162:165], v[202:205], v[42:45]
	v_mfma_f32_16x16x32_bf16 v[114:117], v[136:139], v[210:213], v[116:119]
	v_mfma_f32_16x16x32_bf16 v[38:41], v[162:165], v[210:213], v[38:41]
	v_mfma_f32_16x16x32_bf16 v[120:123], v[158:161], v[174:177], v[120:123]
	v_mfma_f32_16x16x32_bf16 v[94:97], v[166:169], v[174:177], v[94:97]
	v_mfma_f32_16x16x32_bf16 v[150:153], v[158:161], v[198:201], v[150:153]
	v_mfma_f32_16x16x32_bf16 v[50:53], v[166:169], v[198:201], v[50:53]
	v_mfma_f32_16x16x32_bf16 v[140:143], v[158:161], v[206:209], v[140:143]
	v_mfma_f32_16x16x32_bf16 v[42:45], v[166:169], v[206:209], v[42:45]
	v_mfma_f32_16x16x32_bf16 v[114:117], v[158:161], v[214:217], v[114:117]
	v_mfma_f32_16x16x32_bf16 v[38:41], v[166:169], v[214:217], v[38:41]
	s_setprio 0
	s_barrier
	s_add_i32 s76, s76, s42
	s_mov_b32 m0, s76
	ds_read_b128 v[170:173], v234 offset:16384
	ds_read_b128 v[174:177], v234 offset:17408
	ds_read_b128 v[178:181], v234 offset:18432
	ds_read_b128 v[198:201], v234 offset:19456
	ds_read_b128 v[202:205], v234 offset:20480
	ds_read_b128 v[206:209], v234 offset:21504
	ds_read_b128 v[210:213], v234 offset:22528
	ds_read_b128 v[214:217], v234 offset:23552
	global_load_lds_dwordx4 v0, s[24:25]
	s_add_i32 m0, s76, 0x2000
	s_add_u32 s76, s24, 0x40000
	s_addc_u32 s77, s25, 0
	s_add_i32 vcc_hi, vcc_hi, s42
	global_load_lds_dwordx4 v192, s[24:25]
	s_mov_b32 m0, vcc_hi
	s_nop 0
	global_load_lds_dwordx4 v0, s[76:77]
	s_add_i32 m0, vcc_hi, 0x2000
	s_nop 0
	global_load_lds_dwordx4 v192, s[76:77]
	s_mov_b32 m0, s57
	s_nop 0
	global_load_lds_dwordx4 v188, s[28:29]
	s_mov_b32 m0, s66
	s_nop 0
	global_load_lds_dwordx4 v190, s[28:29]
	s_waitcnt vmcnt(8)
	s_waitcnt lgkmcnt(0)
	s_barrier
	s_setprio 1
	v_mfma_f32_16x16x32_bf16 v[86:89], v[106:109], v[170:173], v[86:89]
	v_mfma_f32_16x16x32_bf16 v[30:33], v[128:131], v[170:173], v[30:33]
	v_mfma_f32_16x16x32_bf16 v[78:81], v[106:109], v[178:181], v[78:81]
	v_mfma_f32_16x16x32_bf16 v[22:25], v[128:131], v[178:181], v[22:25]
	v_mfma_f32_16x16x32_bf16 v[70:73], v[106:109], v[202:205], v[70:73]
	v_mfma_f32_16x16x32_bf16 v[14:17], v[128:131], v[202:205], v[14:17]
	v_mfma_f32_16x16x32_bf16 v[90:93], v[106:109], v[210:213], v[90:93]
	v_mfma_f32_16x16x32_bf16 v[34:37], v[128:131], v[210:213], v[34:37]
	v_mfma_f32_16x16x32_bf16 v[86:89], v[110:113], v[174:177], v[86:89]
	v_mfma_f32_16x16x32_bf16 v[30:33], v[132:135], v[174:177], v[30:33]
	v_mfma_f32_16x16x32_bf16 v[78:81], v[110:113], v[198:201], v[78:81]
	v_mfma_f32_16x16x32_bf16 v[22:25], v[132:135], v[198:201], v[22:25]
	v_mfma_f32_16x16x32_bf16 v[70:73], v[110:113], v[206:209], v[70:73]
	v_mfma_f32_16x16x32_bf16 v[14:17], v[132:135], v[206:209], v[14:17]
	v_mfma_f32_16x16x32_bf16 v[90:93], v[110:113], v[214:217], v[90:93]
	v_mfma_f32_16x16x32_bf16 v[34:37], v[132:135], v[214:217], v[34:37]
	v_mfma_f32_16x16x32_bf16 v[82:85], v[136:139], v[170:173], v[82:85]
	v_mfma_f32_16x16x32_bf16 v[26:29], v[162:165], v[170:173], v[26:29]
	v_mfma_f32_16x16x32_bf16 v[74:77], v[136:139], v[178:181], v[74:77]
	v_mfma_f32_16x16x32_bf16 v[18:21], v[162:165], v[178:181], v[18:21]
	v_mfma_f32_16x16x32_bf16 v[66:69], v[136:139], v[202:205], v[66:69]
	v_mfma_f32_16x16x32_bf16 v[10:13], v[162:165], v[202:205], v[10:13]
	v_mfma_f32_16x16x32_bf16 v[62:65], v[136:139], v[210:213], v[62:65]
	v_mfma_f32_16x16x32_bf16 v[6:9], v[162:165], v[210:213], v[6:9]
	v_mfma_f32_16x16x32_bf16 v[82:85], v[158:161], v[174:177], v[82:85]
	v_mfma_f32_16x16x32_bf16 v[26:29], v[166:169], v[174:177], v[26:29]
	v_mfma_f32_16x16x32_bf16 v[74:77], v[158:161], v[198:201], v[74:77]
	v_mfma_f32_16x16x32_bf16 v[18:21], v[166:169], v[198:201], v[18:21]
	v_mfma_f32_16x16x32_bf16 v[66:69], v[158:161], v[206:209], v[66:69]
	v_mfma_f32_16x16x32_bf16 v[10:13], v[166:169], v[206:209], v[10:13]
	v_mfma_f32_16x16x32_bf16 v[62:65], v[158:161], v[214:217], v[62:65]
	v_mfma_f32_16x16x32_bf16 v[6:9], v[166:169], v[214:217], v[6:9]
	s_setprio 0
	s_barrier
	s_add_i32 s76, 0, 0x18000
	v_add_u32_e32 v118, s76, v220
	s_add_i32 s77, 0, 0x1c000
	ds_read_b128 v[106:109], v118
	ds_read_b128 v[110:113], v118 offset:1024
	ds_read_b128 v[128:131], v118 offset:2048
	ds_read_b128 v[132:135], v118 offset:3072
	v_add_u32_e32 v118, s77, v220
	ds_read_b128 v[136:139], v118
	ds_read_b128 v[158:161], v118 offset:1024
	ds_read_b128 v[162:165], v118 offset:2048
	ds_read_b128 v[166:169], v118 offset:3072
	s_add_u32 s28, s28, 0x40000
	s_addc_u32 s29, s29, 0
	s_mov_b32 m0, s67
	ds_read_b128 v[170:173], v234 offset:32768
	ds_read_b128 v[174:177], v234 offset:33792
	ds_read_b128 v[178:181], v234 offset:34816
	ds_read_b128 v[198:201], v234 offset:35840
	ds_read_b128 v[202:205], v234 offset:36864
	ds_read_b128 v[206:209], v234 offset:37888
	ds_read_b128 v[210:213], v234 offset:38912
	ds_read_b128 v[214:217], v234 offset:39936
	global_load_lds_dwordx4 v188, s[28:29]
	s_mov_b32 m0, s44
	s_nop 0
	global_load_lds_dwordx4 v190, s[28:29]
	s_waitcnt vmcnt(8)
	s_waitcnt lgkmcnt(0)
	s_barrier
	s_setprio 1
	v_mfma_f32_16x16x32_bf16 v[124:127], v[106:109], v[170:173], v[124:127]
	v_mfma_f32_16x16x32_bf16 v[98:101], v[128:131], v[170:173], v[98:101]
	v_mfma_f32_16x16x32_bf16 v[154:157], v[106:109], v[178:181], v[154:157]
	v_mfma_f32_16x16x32_bf16 v[58:61], v[128:131], v[178:181], v[58:61]
	v_mfma_f32_16x16x32_bf16 v[144:147], v[106:109], v[202:205], v[146:149]
	v_mfma_f32_16x16x32_bf16 v[46:49], v[128:131], v[202:205], v[46:49]
	v_mfma_f32_16x16x32_bf16 v[102:105], v[106:109], v[210:213], v[102:105]
	v_mfma_f32_16x16x32_bf16 v[54:57], v[128:131], v[210:213], v[54:57]
	v_mfma_f32_16x16x32_bf16 v[124:127], v[110:113], v[174:177], v[124:127]
	v_mfma_f32_16x16x32_bf16 v[98:101], v[132:135], v[174:177], v[98:101]
	v_mfma_f32_16x16x32_bf16 v[154:157], v[110:113], v[198:201], v[154:157]
	v_mfma_f32_16x16x32_bf16 v[58:61], v[132:135], v[198:201], v[58:61]
	v_mfma_f32_16x16x32_bf16 v[146:149], v[110:113], v[206:209], v[144:147]
	v_mfma_f32_16x16x32_bf16 v[46:49], v[132:135], v[206:209], v[46:49]
	v_mfma_f32_16x16x32_bf16 v[102:105], v[110:113], v[214:217], v[102:105]
	v_mfma_f32_16x16x32_bf16 v[54:57], v[132:135], v[214:217], v[54:57]
	v_mfma_f32_16x16x32_bf16 v[118:121], v[136:139], v[170:173], v[120:123]
	v_mfma_f32_16x16x32_bf16 v[94:97], v[162:165], v[170:173], v[94:97]
	v_mfma_f32_16x16x32_bf16 v[150:153], v[136:139], v[178:181], v[150:153]
	v_mfma_f32_16x16x32_bf16 v[50:53], v[162:165], v[178:181], v[50:53]
	v_mfma_f32_16x16x32_bf16 v[140:143], v[136:139], v[202:205], v[140:143]
	v_mfma_f32_16x16x32_bf16 v[42:45], v[162:165], v[202:205], v[42:45]
	v_mfma_f32_16x16x32_bf16 v[114:117], v[136:139], v[210:213], v[114:117]
	v_mfma_f32_16x16x32_bf16 v[38:41], v[162:165], v[210:213], v[38:41]
	v_mfma_f32_16x16x32_bf16 v[120:123], v[158:161], v[174:177], v[118:121]
	v_mfma_f32_16x16x32_bf16 v[94:97], v[166:169], v[174:177], v[94:97]
	v_mfma_f32_16x16x32_bf16 v[150:153], v[158:161], v[198:201], v[150:153]
	v_mfma_f32_16x16x32_bf16 v[50:53], v[166:169], v[198:201], v[50:53]
	v_mfma_f32_16x16x32_bf16 v[142:145], v[158:161], v[206:209], v[140:143]
	v_mfma_f32_16x16x32_bf16 v[42:45], v[166:169], v[206:209], v[42:45]
	v_mfma_f32_16x16x32_bf16 v[116:119], v[158:161], v[214:217], v[114:117]
	v_mfma_f32_16x16x32_bf16 v[38:41], v[166:169], v[214:217], v[38:41]
	s_setprio 0
	s_barrier
	s_add_i32 s100, s76, s42
	s_mov_b32 m0, s100
	ds_read_b128 v[170:173], v234 offset:49152
	ds_read_b128 v[174:177], v234 offset:50176
	ds_read_b128 v[178:181], v234 offset:51200
	ds_read_b128 v[198:201], v234 offset:52224
	ds_read_b128 v[202:205], v234 offset:53248
	ds_read_b128 v[206:209], v234 offset:54272
	ds_read_b128 v[210:213], v234 offset:55296
	ds_read_b128 v[214:217], v234 offset:56320
	s_add_u32 s24, s24, 0x80
	s_addc_u32 s25, s25, 0
	global_load_lds_dwordx4 v0, s[24:25]
	s_add_i32 m0, s100, 0x2000
	s_add_i32 s100, s77, s42
	global_load_lds_dwordx4 v192, s[24:25]
	s_add_u32 s24, s24, 0x40000
	s_addc_u32 s25, s25, 0
	s_mov_b32 m0, s100
	s_add_i32 s100, s100, 0x2000
	global_load_lds_dwordx4 v0, s[24:25]
	s_mov_b32 m0, s100
	s_add_u32 s28, s28, 0xfffc0080
	s_addc_u32 s29, s29, -1
	global_load_lds_dwordx4 v192, s[24:25]
	s_mov_b32 m0, s45
	s_nop 0
	global_load_lds_dwordx4 v188, s[28:29]
	s_mov_b32 m0, s70
	s_nop 0
	global_load_lds_dwordx4 v190, s[28:29]
	s_waitcnt vmcnt(8)
	s_waitcnt lgkmcnt(0)
	s_barrier
	s_setprio 1
	v_mfma_f32_16x16x32_bf16 v[86:89], v[106:109], v[170:173], v[86:89]
	v_mfma_f32_16x16x32_bf16 v[30:33], v[128:131], v[170:173], v[30:33]
	v_mfma_f32_16x16x32_bf16 v[78:81], v[106:109], v[178:181], v[78:81]
	v_mfma_f32_16x16x32_bf16 v[22:25], v[128:131], v[178:181], v[22:25]
	v_mfma_f32_16x16x32_bf16 v[70:73], v[106:109], v[202:205], v[70:73]
	v_mfma_f32_16x16x32_bf16 v[14:17], v[128:131], v[202:205], v[14:17]
	v_mfma_f32_16x16x32_bf16 v[90:93], v[106:109], v[210:213], v[90:93]
	v_mfma_f32_16x16x32_bf16 v[34:37], v[128:131], v[210:213], v[34:37]
	v_mfma_f32_16x16x32_bf16 v[86:89], v[110:113], v[174:177], v[86:89]
	v_mfma_f32_16x16x32_bf16 v[30:33], v[132:135], v[174:177], v[30:33]
	v_mfma_f32_16x16x32_bf16 v[78:81], v[110:113], v[198:201], v[78:81]
	v_mfma_f32_16x16x32_bf16 v[22:25], v[132:135], v[198:201], v[22:25]
	v_mfma_f32_16x16x32_bf16 v[70:73], v[110:113], v[206:209], v[70:73]
	v_mfma_f32_16x16x32_bf16 v[14:17], v[132:135], v[206:209], v[14:17]
	v_mfma_f32_16x16x32_bf16 v[90:93], v[110:113], v[214:217], v[90:93]
	v_mfma_f32_16x16x32_bf16 v[34:37], v[132:135], v[214:217], v[34:37]
	v_mfma_f32_16x16x32_bf16 v[82:85], v[136:139], v[170:173], v[82:85]
	v_mfma_f32_16x16x32_bf16 v[26:29], v[162:165], v[170:173], v[26:29]
	v_mfma_f32_16x16x32_bf16 v[74:77], v[136:139], v[178:181], v[74:77]
	v_mfma_f32_16x16x32_bf16 v[18:21], v[162:165], v[178:181], v[18:21]
	v_mfma_f32_16x16x32_bf16 v[66:69], v[136:139], v[202:205], v[66:69]
	v_mfma_f32_16x16x32_bf16 v[10:13], v[162:165], v[202:205], v[10:13]
	v_mfma_f32_16x16x32_bf16 v[62:65], v[136:139], v[210:213], v[62:65]
	v_mfma_f32_16x16x32_bf16 v[6:9], v[162:165], v[210:213], v[6:9]
	v_mfma_f32_16x16x32_bf16 v[82:85], v[158:161], v[174:177], v[82:85]
	v_mfma_f32_16x16x32_bf16 v[26:29], v[166:169], v[174:177], v[26:29]
	v_mfma_f32_16x16x32_bf16 v[74:77], v[158:161], v[198:201], v[74:77]
	v_mfma_f32_16x16x32_bf16 v[18:21], v[166:169], v[198:201], v[18:21]
	v_mfma_f32_16x16x32_bf16 v[66:69], v[158:161], v[206:209], v[66:69]
	v_mfma_f32_16x16x32_bf16 v[10:13], v[166:169], v[206:209], v[10:13]
	v_mfma_f32_16x16x32_bf16 v[62:65], v[158:161], v[214:217], v[62:65]
	v_mfma_f32_16x16x32_bf16 v[6:9], v[166:169], v[214:217], v[6:9]
	s_setprio 0
	s_barrier
	s_add_i32 vcc_lo, vcc_lo, 2
	s_add_u32 s22, s22, 0x100
	s_addc_u32 s23, s23, 0
	s_add_u32 s81, s81, 0x100
	s_addc_u32 s99, s99, 0
	s_cmp_gt_u32 vcc_lo, 13
	s_cbranch_scc0 .LBB0_453
	s_and_b64 vcc, exec, s[26:27]
	s_cbranch_vccz .LBB0_456
	s_barrier

.LBB0_711:
	s_add_u32 s8, s10, 0xfffc0080
	s_addc_u32 s9, s11, -1
	s_add_i32 s67, 0, 0x10000
	s_cmp_eq_u32 s51, 12
	s_cselect_b32 s13, s25, s9
	s_cselect_b32 s12, s27, s8
	s_cselect_b32 s9, s29, s50
	s_cselect_b32 s8, s44, s45
	s_add_i32 s72, 0, 0x14000
	v_add_u32_e32 v146, s67, v245
	v_add_u32_e32 v162, s72, v245
	ds_read_b128 v[134:137], v146
	ds_read_b128 v[138:141], v146 offset:1024
	ds_read_b128 v[142:145], v146 offset:2048
	ds_read_b128 v[146:149], v146 offset:3072
	ds_read_b128 v[150:153], v162
	ds_read_b128 v[154:157], v162 offset:1024
	ds_read_b128 v[158:161], v162 offset:2048
	ds_read_b128 v[162:165], v162 offset:3072
	s_add_i32 m0, s68, 0xc000
	ds_read_b128 v[166:169], v247
	ds_read_b128 v[170:173], v247 offset:1024
	ds_read_b128 v[174:177], v247 offset:2048
	ds_read_b128 v[178:181], v247 offset:3072
	ds_read_b128 v[196:199], v247 offset:4096
	ds_read_b128 v[200:203], v247 offset:5120
	ds_read_b128 v[204:207], v247 offset:6144
	ds_read_b128 v[208:211], v247 offset:7168
	global_load_lds_dwordx4 v192, s[10:11]
	s_add_i32 m0, s68, 0xe000
	s_nop 0
	global_load_lds_dwordx4 v194, s[10:11]
	s_waitcnt vmcnt(8)
	s_waitcnt lgkmcnt(0)
	s_barrier
	s_setprio 1
	v_mfma_f32_16x16x32_bf16 v[130:133], v[134:137], v[166:169], v[130:133]
	v_mfma_f32_16x16x32_bf16 v[126:129], v[142:145], v[166:169], v[126:129]
	v_mfma_f32_16x16x32_bf16 v[114:117], v[134:137], v[174:177], v[114:117]
	v_mfma_f32_16x16x32_bf16 v[110:113], v[142:145], v[174:177], v[110:113]
	v_mfma_f32_16x16x32_bf16 v[98:101], v[134:137], v[196:199], v[98:101]
	v_mfma_f32_16x16x32_bf16 v[94:97], v[142:145], v[196:199], v[94:97]
	v_mfma_f32_16x16x32_bf16 v[82:85], v[134:137], v[204:207], v[82:85]
	v_mfma_f32_16x16x32_bf16 v[78:81], v[142:145], v[204:207], v[78:81]
	v_mfma_f32_16x16x32_bf16 v[130:133], v[138:141], v[170:173], v[130:133]
	v_mfma_f32_16x16x32_bf16 v[126:129], v[146:149], v[170:173], v[126:129]
	v_mfma_f32_16x16x32_bf16 v[114:117], v[138:141], v[178:181], v[114:117]
	v_mfma_f32_16x16x32_bf16 v[110:113], v[146:149], v[178:181], v[110:113]
	v_mfma_f32_16x16x32_bf16 v[98:101], v[138:141], v[200:203], v[98:101]
	v_mfma_f32_16x16x32_bf16 v[94:97], v[146:149], v[200:203], v[94:97]
	v_mfma_f32_16x16x32_bf16 v[82:85], v[138:141], v[208:211], v[82:85]
	v_mfma_f32_16x16x32_bf16 v[78:81], v[146:149], v[208:211], v[78:81]
	v_mfma_f32_16x16x32_bf16 v[122:125], v[150:153], v[166:169], v[122:125]
	v_mfma_f32_16x16x32_bf16 v[118:121], v[158:161], v[166:169], v[118:121]
	v_mfma_f32_16x16x32_bf16 v[106:109], v[150:153], v[174:177], v[106:109]
	v_mfma_f32_16x16x32_bf16 v[102:105], v[158:161], v[174:177], v[102:105]
	v_mfma_f32_16x16x32_bf16 v[90:93], v[150:153], v[196:199], v[90:93]
	v_mfma_f32_16x16x32_bf16 v[86:89], v[158:161], v[196:199], v[86:89]
	v_mfma_f32_16x16x32_bf16 v[74:77], v[150:153], v[204:207], v[74:77]
	v_mfma_f32_16x16x32_bf16 v[70:73], v[158:161], v[204:207], v[70:73]
	v_mfma_f32_16x16x32_bf16 v[122:125], v[154:157], v[170:173], v[122:125]
	v_mfma_f32_16x16x32_bf16 v[118:121], v[162:165], v[170:173], v[118:121]
	v_mfma_f32_16x16x32_bf16 v[106:109], v[154:157], v[178:181], v[106:109]
	v_mfma_f32_16x16x32_bf16 v[102:105], v[162:165], v[178:181], v[102:105]
	v_mfma_f32_16x16x32_bf16 v[90:93], v[154:157], v[200:203], v[90:93]
	v_mfma_f32_16x16x32_bf16 v[86:89], v[162:165], v[200:203], v[86:89]
	v_mfma_f32_16x16x32_bf16 v[74:77], v[154:157], v[208:211], v[74:77]
	v_mfma_f32_16x16x32_bf16 v[70:73], v[162:165], v[208:211], v[70:73]
	s_setprio 0
	s_barrier
	s_add_i32 s67, s67, s63
	s_mov_b32 m0, s67
	ds_read_b128 v[166:169], v247 offset:16384
	ds_read_b128 v[170:173], v247 offset:17408
	ds_read_b128 v[174:177], v247 offset:18432
	ds_read_b128 v[178:181], v247 offset:19456
	ds_read_b128 v[196:199], v247 offset:20480
	ds_read_b128 v[200:203], v247 offset:21504
	ds_read_b128 v[204:207], v247 offset:22528
	ds_read_b128 v[208:211], v247 offset:23552
	global_load_lds_dwordx4 v0, s[8:9]
	s_add_i32 m0, s67, 0x2000
	s_add_u32 s70, s8, 0x40000
	s_addc_u32 s71, s9, 0
	s_add_i32 s67, s72, s63
	global_load_lds_dwordx4 v190, s[8:9]
	s_mov_b32 m0, s67
	s_nop 0
	global_load_lds_dwordx4 v0, s[70:71]
	s_add_i32 m0, s67, 0x2000
	s_nop 0
	global_load_lds_dwordx4 v190, s[70:71]
	s_mov_b32 m0, s68
	s_nop 0
	global_load_lds_dwordx4 v182, s[12:13]
	s_mov_b32 m0, s69
	s_nop 0
	global_load_lds_dwordx4 v188, s[12:13]
	s_waitcnt vmcnt(8)
	s_waitcnt lgkmcnt(0)
	s_barrier
	s_setprio 1
	v_mfma_f32_16x16x32_bf16 v[66:69], v[134:137], v[166:169], v[66:69]
	v_mfma_f32_16x16x32_bf16 v[62:65], v[142:145], v[166:169], v[62:65]
	v_mfma_f32_16x16x32_bf16 v[50:53], v[134:137], v[174:177], v[50:53]
	v_mfma_f32_16x16x32_bf16 v[46:49], v[142:145], v[174:177], v[46:49]
	v_mfma_f32_16x16x32_bf16 v[34:37], v[134:137], v[196:199], v[34:37]
	v_mfma_f32_16x16x32_bf16 v[30:33], v[142:145], v[196:199], v[30:33]
	v_mfma_f32_16x16x32_bf16 v[18:21], v[134:137], v[204:207], v[18:21]
	v_mfma_f32_16x16x32_bf16 v[14:17], v[142:145], v[204:207], v[14:17]
	v_mfma_f32_16x16x32_bf16 v[66:69], v[138:141], v[170:173], v[66:69]
	v_mfma_f32_16x16x32_bf16 v[62:65], v[146:149], v[170:173], v[62:65]
	v_mfma_f32_16x16x32_bf16 v[50:53], v[138:141], v[178:181], v[50:53]
	v_mfma_f32_16x16x32_bf16 v[46:49], v[146:149], v[178:181], v[46:49]
	v_mfma_f32_16x16x32_bf16 v[34:37], v[138:141], v[200:203], v[34:37]
	v_mfma_f32_16x16x32_bf16 v[30:33], v[146:149], v[200:203], v[30:33]
	v_mfma_f32_16x16x32_bf16 v[18:21], v[138:141], v[208:211], v[18:21]
	v_mfma_f32_16x16x32_bf16 v[14:17], v[146:149], v[208:211], v[14:17]
	v_mfma_f32_16x16x32_bf16 v[58:61], v[150:153], v[166:169], v[58:61]
	v_mfma_f32_16x16x32_bf16 v[54:57], v[158:161], v[166:169], v[54:57]
	v_mfma_f32_16x16x32_bf16 v[42:45], v[150:153], v[174:177], v[42:45]
	v_mfma_f32_16x16x32_bf16 v[38:41], v[158:161], v[174:177], v[38:41]
	v_mfma_f32_16x16x32_bf16 v[26:29], v[150:153], v[196:199], v[26:29]
	v_mfma_f32_16x16x32_bf16 v[22:25], v[158:161], v[196:199], v[22:25]
	v_mfma_f32_16x16x32_bf16 v[10:13], v[150:153], v[204:207], v[10:13]
	v_mfma_f32_16x16x32_bf16 v[6:9], v[158:161], v[204:207], v[6:9]
	v_mfma_f32_16x16x32_bf16 v[58:61], v[154:157], v[170:173], v[58:61]
	v_mfma_f32_16x16x32_bf16 v[54:57], v[162:165], v[170:173], v[54:57]
	v_mfma_f32_16x16x32_bf16 v[42:45], v[154:157], v[178:181], v[42:45]
	v_mfma_f32_16x16x32_bf16 v[38:41], v[162:165], v[178:181], v[38:41]
	v_mfma_f32_16x16x32_bf16 v[26:29], v[154:157], v[200:203], v[26:29]
	v_mfma_f32_16x16x32_bf16 v[22:25], v[162:165], v[200:203], v[22:25]
	v_mfma_f32_16x16x32_bf16 v[10:13], v[154:157], v[208:211], v[10:13]
	v_mfma_f32_16x16x32_bf16 v[6:9], v[162:165], v[208:211], v[6:9]
	s_setprio 0
	s_barrier
	s_add_i32 s67, 0, 0x18000
	s_add_i32 s70, 0, 0x1c000
	v_add_u32_e32 v146, s67, v245
	v_add_u32_e32 v162, s70, v245
	ds_read_b128 v[134:137], v146
	ds_read_b128 v[138:141], v146 offset:1024
	ds_read_b128 v[142:145], v146 offset:2048
	ds_read_b128 v[146:149], v146 offset:3072
	ds_read_b128 v[150:153], v162
	ds_read_b128 v[154:157], v162 offset:1024
	ds_read_b128 v[158:161], v162 offset:2048
	ds_read_b128 v[162:165], v162 offset:3072
	s_add_u32 s12, s12, 0x40000
	s_addc_u32 s13, s13, 0
	s_mov_b32 m0, s78
	ds_read_b128 v[166:169], v247 offset:32768
	ds_read_b128 v[170:173], v247 offset:33792
	ds_read_b128 v[174:177], v247 offset:34816
	ds_read_b128 v[178:181], v247 offset:35840
	ds_read_b128 v[196:199], v247 offset:36864
	ds_read_b128 v[200:203], v247 offset:37888
	ds_read_b128 v[204:207], v247 offset:38912
	ds_read_b128 v[208:211], v247 offset:39936
	global_load_lds_dwordx4 v182, s[12:13]
	s_mov_b32 m0, s79
	s_nop 0
	global_load_lds_dwordx4 v188, s[12:13]
	s_waitcnt vmcnt(8)
	s_waitcnt lgkmcnt(0)
	s_barrier
	s_setprio 1
	v_mfma_f32_16x16x32_bf16 v[130:133], v[134:137], v[166:169], v[130:133]
	v_mfma_f32_16x16x32_bf16 v[126:129], v[142:145], v[166:169], v[126:129]
	v_mfma_f32_16x16x32_bf16 v[114:117], v[134:137], v[174:177], v[114:117]
	v_mfma_f32_16x16x32_bf16 v[110:113], v[142:145], v[174:177], v[110:113]
	v_mfma_f32_16x16x32_bf16 v[98:101], v[134:137], v[196:199], v[98:101]
	v_mfma_f32_16x16x32_bf16 v[94:97], v[142:145], v[196:199], v[94:97]
	v_mfma_f32_16x16x32_bf16 v[82:85], v[134:137], v[204:207], v[82:85]
	v_mfma_f32_16x16x32_bf16 v[78:81], v[142:145], v[204:207], v[78:81]
	v_mfma_f32_16x16x32_bf16 v[130:133], v[138:141], v[170:173], v[130:133]
	v_mfma_f32_16x16x32_bf16 v[126:129], v[146:149], v[170:173], v[126:129]
	v_mfma_f32_16x16x32_bf16 v[114:117], v[138:141], v[178:181], v[114:117]
	v_mfma_f32_16x16x32_bf16 v[110:113], v[146:149], v[178:181], v[110:113]
	v_mfma_f32_16x16x32_bf16 v[98:101], v[138:141], v[200:203], v[98:101]
	v_mfma_f32_16x16x32_bf16 v[94:97], v[146:149], v[200:203], v[94:97]
	v_mfma_f32_16x16x32_bf16 v[82:85], v[138:141], v[208:211], v[82:85]
	v_mfma_f32_16x16x32_bf16 v[78:81], v[146:149], v[208:211], v[78:81]
	v_mfma_f32_16x16x32_bf16 v[122:125], v[150:153], v[166:169], v[122:125]
	v_mfma_f32_16x16x32_bf16 v[118:121], v[158:161], v[166:169], v[118:121]
	v_mfma_f32_16x16x32_bf16 v[106:109], v[150:153], v[174:177], v[106:109]
	v_mfma_f32_16x16x32_bf16 v[102:105], v[158:161], v[174:177], v[102:105]
	v_mfma_f32_16x16x32_bf16 v[90:93], v[150:153], v[196:199], v[90:93]
	v_mfma_f32_16x16x32_bf16 v[86:89], v[158:161], v[196:199], v[86:89]
	v_mfma_f32_16x16x32_bf16 v[74:77], v[150:153], v[204:207], v[74:77]
	v_mfma_f32_16x16x32_bf16 v[70:73], v[158:161], v[204:207], v[70:73]
	v_mfma_f32_16x16x32_bf16 v[122:125], v[154:157], v[170:173], v[122:125]
	v_mfma_f32_16x16x32_bf16 v[118:121], v[162:165], v[170:173], v[118:121]
	v_mfma_f32_16x16x32_bf16 v[106:109], v[154:157], v[178:181], v[106:109]
	v_mfma_f32_16x16x32_bf16 v[102:105], v[162:165], v[178:181], v[102:105]
	v_mfma_f32_16x16x32_bf16 v[90:93], v[154:157], v[200:203], v[90:93]
	v_mfma_f32_16x16x32_bf16 v[86:89], v[162:165], v[200:203], v[86:89]
	v_mfma_f32_16x16x32_bf16 v[74:77], v[154:157], v[208:211], v[74:77]
	v_mfma_f32_16x16x32_bf16 v[70:73], v[162:165], v[208:211], v[70:73]
	s_setprio 0
	s_barrier
	s_add_i32 s100, s67, s63
	s_mov_b32 m0, s100
	ds_read_b128 v[166:169], v247 offset:49152
	ds_read_b128 v[170:173], v247 offset:50176
	ds_read_b128 v[174:177], v247 offset:51200
	ds_read_b128 v[178:181], v247 offset:52224
	ds_read_b128 v[196:199], v247 offset:53248
	ds_read_b128 v[200:203], v247 offset:54272
	ds_read_b128 v[204:207], v247 offset:55296
	ds_read_b128 v[208:211], v247 offset:56320
	s_add_u32 s8, s8, 0x80
	s_addc_u32 s9, s9, 0
	global_load_lds_dwordx4 v0, s[8:9]
	s_add_i32 m0, s100, 0x2000
	s_add_i32 s100, s70, s63
	global_load_lds_dwordx4 v190, s[8:9]
	s_add_u32 s8, s8, 0x40000
	s_addc_u32 s9, s9, 0
	s_mov_b32 m0, s100
	s_add_i32 s100, s100, 0x2000
	global_load_lds_dwordx4 v0, s[8:9]
	s_mov_b32 m0, s100
	s_add_u32 s12, s12, 0xfffc0080
	s_addc_u32 s13, s13, -1
	global_load_lds_dwordx4 v190, s[8:9]
	s_mov_b32 m0, s80
	s_nop 0
	global_load_lds_dwordx4 v182, s[12:13]
	s_mov_b32 m0, s81
	s_nop 0
	global_load_lds_dwordx4 v188, s[12:13]
	s_waitcnt vmcnt(8)
	s_waitcnt lgkmcnt(0)
	s_barrier
	s_setprio 1
	v_mfma_f32_16x16x32_bf16 v[66:69], v[134:137], v[166:169], v[66:69]
	v_mfma_f32_16x16x32_bf16 v[62:65], v[142:145], v[166:169], v[62:65]
	v_mfma_f32_16x16x32_bf16 v[50:53], v[134:137], v[174:177], v[50:53]
	v_mfma_f32_16x16x32_bf16 v[46:49], v[142:145], v[174:177], v[46:49]
	v_mfma_f32_16x16x32_bf16 v[34:37], v[134:137], v[196:199], v[34:37]
	v_mfma_f32_16x16x32_bf16 v[30:33], v[142:145], v[196:199], v[30:33]
	v_mfma_f32_16x16x32_bf16 v[18:21], v[134:137], v[204:207], v[18:21]
	v_mfma_f32_16x16x32_bf16 v[14:17], v[142:145], v[204:207], v[14:17]
	v_mfma_f32_16x16x32_bf16 v[66:69], v[138:141], v[170:173], v[66:69]
	v_mfma_f32_16x16x32_bf16 v[62:65], v[146:149], v[170:173], v[62:65]
	v_mfma_f32_16x16x32_bf16 v[50:53], v[138:141], v[178:181], v[50:53]
	v_mfma_f32_16x16x32_bf16 v[46:49], v[146:149], v[178:181], v[46:49]
	v_mfma_f32_16x16x32_bf16 v[34:37], v[138:141], v[200:203], v[34:37]
	v_mfma_f32_16x16x32_bf16 v[30:33], v[146:149], v[200:203], v[30:33]
	v_mfma_f32_16x16x32_bf16 v[18:21], v[138:141], v[208:211], v[18:21]
	v_mfma_f32_16x16x32_bf16 v[14:17], v[146:149], v[208:211], v[14:17]
	v_mfma_f32_16x16x32_bf16 v[58:61], v[150:153], v[166:169], v[58:61]
	v_mfma_f32_16x16x32_bf16 v[54:57], v[158:161], v[166:169], v[54:57]
	v_mfma_f32_16x16x32_bf16 v[42:45], v[150:153], v[174:177], v[42:45]
	v_mfma_f32_16x16x32_bf16 v[38:41], v[158:161], v[174:177], v[38:41]
	v_mfma_f32_16x16x32_bf16 v[26:29], v[150:153], v[196:199], v[26:29]
	v_mfma_f32_16x16x32_bf16 v[22:25], v[158:161], v[196:199], v[22:25]
	v_mfma_f32_16x16x32_bf16 v[10:13], v[150:153], v[204:207], v[10:13]
	v_mfma_f32_16x16x32_bf16 v[6:9], v[158:161], v[204:207], v[6:9]
	v_mfma_f32_16x16x32_bf16 v[58:61], v[154:157], v[170:173], v[58:61]
	v_mfma_f32_16x16x32_bf16 v[54:57], v[162:165], v[170:173], v[54:57]
	v_mfma_f32_16x16x32_bf16 v[42:45], v[154:157], v[178:181], v[42:45]
	v_mfma_f32_16x16x32_bf16 v[38:41], v[162:165], v[178:181], v[38:41]
	v_mfma_f32_16x16x32_bf16 v[26:29], v[154:157], v[200:203], v[26:29]
	v_mfma_f32_16x16x32_bf16 v[22:25], v[162:165], v[200:203], v[22:25]
	v_mfma_f32_16x16x32_bf16 v[10:13], v[154:157], v[208:211], v[10:13]
	v_mfma_f32_16x16x32_bf16 v[6:9], v[162:165], v[208:211], v[6:9]
	s_setprio 0
	s_barrier
	s_add_i32 s51, s51, 2
	s_add_u32 s10, s10, 0x100
	s_addc_u32 s11, s11, 0
	s_add_u32 s45, s45, 0x100
	s_addc_u32 s50, s50, 0
	s_cmp_gt_u32 s51, 13
	s_cbranch_scc0 .LBB0_711
	s_and_b64 vcc, exec, s[20:21]
	s_cbranch_vccz .LBB0_714
	s_barrier

.LBB0_1065:
	s_add_i32 s44, s26, 2
	s_add_u32 s45, s10, 0x80
	s_addc_u32 s27, s11, 0
	s_add_i32 s72, 0, 0x10000
	s_cmp_eq_u32 s68, s26
	s_cselect_b32 s27, s25, s27
	s_cselect_b32 s26, s24, s45
	s_cselect_b32 s71, s29, s31
	s_cselect_b32 s70, s28, s30
	s_add_i32 s45, 0, 0x14000
	v_add_u32_e32 v114, s72, v217
	v_add_u32_e32 v162, s45, v217
	ds_read_b128 v[94:97], v114
	ds_read_b128 v[102:105], v114 offset:1024
	ds_read_b128 v[110:113], v114 offset:2048
	ds_read_b128 v[114:117], v114 offset:3072
	ds_read_b128 v[150:153], v162
	ds_read_b128 v[154:157], v162 offset:1024
	ds_read_b128 v[158:161], v162 offset:2048
	ds_read_b128 v[162:165], v162 offset:3072
	s_add_i32 m0, s57, 0xc000
	ds_read_b128 v[166:169], v236
	ds_read_b128 v[170:173], v236 offset:1024
	ds_read_b128 v[174:177], v236 offset:2048
	ds_read_b128 v[178:181], v236 offset:3072
	ds_read_b128 v[196:199], v236 offset:4096
	ds_read_b128 v[200:203], v236 offset:5120
	ds_read_b128 v[204:207], v236 offset:6144
	ds_read_b128 v[208:211], v236 offset:7168
	global_load_lds_dwordx4 v192, s[10:11]
	s_add_i32 m0, s57, 0xe000
	s_nop 0
	global_load_lds_dwordx4 v194, s[10:11]
	s_waitcnt vmcnt(8)
	s_waitcnt lgkmcnt(0)
	s_barrier
	s_setprio 1
	v_mfma_f32_16x16x32_bf16 v[146:149], v[94:97], v[166:169], v[146:149]
	v_mfma_f32_16x16x32_bf16 v[142:145], v[110:113], v[166:169], v[142:145]
	v_mfma_f32_16x16x32_bf16 v[130:133], v[94:97], v[174:177], v[130:133]
	v_mfma_f32_16x16x32_bf16 v[126:129], v[110:113], v[174:177], v[126:129]
	v_mfma_f32_16x16x32_bf16 v[106:109], v[94:97], v[196:199], v[106:109]
	v_mfma_f32_16x16x32_bf16 v[98:101], v[110:113], v[196:199], v[98:101]
	v_mfma_f32_16x16x32_bf16 v[82:85], v[94:97], v[204:207], v[82:85]
	v_mfma_f32_16x16x32_bf16 v[78:81], v[110:113], v[204:207], v[78:81]
	v_mfma_f32_16x16x32_bf16 v[146:149], v[102:105], v[170:173], v[146:149]
	v_mfma_f32_16x16x32_bf16 v[142:145], v[114:117], v[170:173], v[142:145]
	v_mfma_f32_16x16x32_bf16 v[130:133], v[102:105], v[178:181], v[130:133]
	v_mfma_f32_16x16x32_bf16 v[126:129], v[114:117], v[178:181], v[126:129]
	v_mfma_f32_16x16x32_bf16 v[106:109], v[102:105], v[200:203], v[106:109]
	v_mfma_f32_16x16x32_bf16 v[98:101], v[114:117], v[200:203], v[98:101]
	v_mfma_f32_16x16x32_bf16 v[82:85], v[102:105], v[208:211], v[82:85]
	v_mfma_f32_16x16x32_bf16 v[78:81], v[114:117], v[208:211], v[78:81]
	v_mfma_f32_16x16x32_bf16 v[138:141], v[150:153], v[166:169], v[138:141]
	v_mfma_f32_16x16x32_bf16 v[134:137], v[158:161], v[166:169], v[134:137]
	v_mfma_f32_16x16x32_bf16 v[122:125], v[150:153], v[174:177], v[122:125]
	v_mfma_f32_16x16x32_bf16 v[118:121], v[158:161], v[174:177], v[118:121]
	v_mfma_f32_16x16x32_bf16 v[90:93], v[150:153], v[196:199], v[90:93]
	v_mfma_f32_16x16x32_bf16 v[86:89], v[158:161], v[196:199], v[86:89]
	v_mfma_f32_16x16x32_bf16 v[74:77], v[150:153], v[204:207], v[74:77]
	v_mfma_f32_16x16x32_bf16 v[70:73], v[158:161], v[204:207], v[70:73]
	v_mfma_f32_16x16x32_bf16 v[138:141], v[154:157], v[170:173], v[138:141]
	v_mfma_f32_16x16x32_bf16 v[134:137], v[162:165], v[170:173], v[134:137]
	v_mfma_f32_16x16x32_bf16 v[122:125], v[154:157], v[178:181], v[122:125]
	v_mfma_f32_16x16x32_bf16 v[118:121], v[162:165], v[178:181], v[118:121]
	v_mfma_f32_16x16x32_bf16 v[90:93], v[154:157], v[200:203], v[90:93]
	v_mfma_f32_16x16x32_bf16 v[86:89], v[162:165], v[200:203], v[86:89]
	v_mfma_f32_16x16x32_bf16 v[74:77], v[154:157], v[208:211], v[74:77]
	v_mfma_f32_16x16x32_bf16 v[70:73], v[162:165], v[208:211], v[70:73]
	s_setprio 0
	s_barrier
	s_add_i32 s72, s72, s54
	s_mov_b32 m0, s72
	ds_read_b128 v[166:169], v236 offset:16384
	ds_read_b128 v[170:173], v236 offset:17408
	ds_read_b128 v[174:177], v236 offset:18432
	ds_read_b128 v[178:181], v236 offset:19456
	ds_read_b128 v[196:199], v236 offset:20480
	ds_read_b128 v[200:203], v236 offset:21504
	ds_read_b128 v[204:207], v236 offset:22528
	ds_read_b128 v[208:211], v236 offset:23552
	global_load_lds_dwordx4 v0, s[70:71]
	s_add_i32 m0, s72, 0x2000
	s_add_u32 s100, s70, 0x80
	s_addc_u32 s101, s71, 0
	global_load_lds_dwordx4 v190, s[70:71]
	s_add_u32 s70, s70, s42
	s_addc_u32 s71, s71, 0
	s_add_i32 s45, s45, s54
	s_mov_b32 m0, s45
	s_nop 0
	global_load_lds_dwordx4 v0, s[70:71]
	s_add_i32 m0, s45, 0x2000
	s_nop 0
	global_load_lds_dwordx4 v190, s[70:71]
	s_mov_b32 m0, s57
	s_nop 0
	global_load_lds_dwordx4 v182, s[26:27]
	s_mov_b32 m0, s58
	s_nop 0
	global_load_lds_dwordx4 v188, s[26:27]
	s_waitcnt vmcnt(8)
	s_waitcnt lgkmcnt(0)
	s_barrier
	s_setprio 1
	v_mfma_f32_16x16x32_bf16 v[66:69], v[94:97], v[166:169], v[66:69]
	v_mfma_f32_16x16x32_bf16 v[62:65], v[110:113], v[166:169], v[62:65]
	v_mfma_f32_16x16x32_bf16 v[50:53], v[94:97], v[174:177], v[50:53]
	v_mfma_f32_16x16x32_bf16 v[46:49], v[110:113], v[174:177], v[46:49]
	v_mfma_f32_16x16x32_bf16 v[34:37], v[94:97], v[196:199], v[34:37]
	v_mfma_f32_16x16x32_bf16 v[30:33], v[110:113], v[196:199], v[30:33]
	v_mfma_f32_16x16x32_bf16 v[18:21], v[94:97], v[204:207], v[18:21]
	v_mfma_f32_16x16x32_bf16 v[14:17], v[110:113], v[204:207], v[14:17]
	v_mfma_f32_16x16x32_bf16 v[66:69], v[102:105], v[170:173], v[66:69]
	v_mfma_f32_16x16x32_bf16 v[62:65], v[114:117], v[170:173], v[62:65]
	v_mfma_f32_16x16x32_bf16 v[50:53], v[102:105], v[178:181], v[50:53]
	v_mfma_f32_16x16x32_bf16 v[46:49], v[114:117], v[178:181], v[46:49]
	v_mfma_f32_16x16x32_bf16 v[34:37], v[102:105], v[200:203], v[34:37]
	v_mfma_f32_16x16x32_bf16 v[30:33], v[114:117], v[200:203], v[30:33]
	v_mfma_f32_16x16x32_bf16 v[18:21], v[102:105], v[208:211], v[18:21]
	v_mfma_f32_16x16x32_bf16 v[14:17], v[114:117], v[208:211], v[14:17]
	v_mfma_f32_16x16x32_bf16 v[58:61], v[150:153], v[166:169], v[58:61]
	v_mfma_f32_16x16x32_bf16 v[54:57], v[158:161], v[166:169], v[54:57]
	v_mfma_f32_16x16x32_bf16 v[42:45], v[150:153], v[174:177], v[42:45]
	v_mfma_f32_16x16x32_bf16 v[38:41], v[158:161], v[174:177], v[38:41]
	v_mfma_f32_16x16x32_bf16 v[26:29], v[150:153], v[196:199], v[26:29]
	v_mfma_f32_16x16x32_bf16 v[22:25], v[158:161], v[196:199], v[22:25]
	v_mfma_f32_16x16x32_bf16 v[10:13], v[150:153], v[204:207], v[10:13]
	v_mfma_f32_16x16x32_bf16 v[6:9], v[158:161], v[204:207], v[6:9]
	v_mfma_f32_16x16x32_bf16 v[58:61], v[154:157], v[170:173], v[58:61]
	v_mfma_f32_16x16x32_bf16 v[54:57], v[162:165], v[170:173], v[54:57]
	v_mfma_f32_16x16x32_bf16 v[42:45], v[154:157], v[178:181], v[42:45]
	v_mfma_f32_16x16x32_bf16 v[38:41], v[162:165], v[178:181], v[38:41]
	v_mfma_f32_16x16x32_bf16 v[26:29], v[154:157], v[200:203], v[26:29]
	v_mfma_f32_16x16x32_bf16 v[22:25], v[162:165], v[200:203], v[22:25]
	v_mfma_f32_16x16x32_bf16 v[10:13], v[154:157], v[208:211], v[10:13]
	v_mfma_f32_16x16x32_bf16 v[6:9], v[162:165], v[208:211], v[6:9]
	s_setprio 0
	s_barrier
	s_add_i32 s45, 0, 0x18000
	v_add_u32_e32 v114, s45, v217
	v_add_u32_e32 v162, 0x1c000, v217
	ds_read_b128 v[94:97], v114
	ds_read_b128 v[102:105], v114 offset:1024
	ds_read_b128 v[110:113], v114 offset:2048
	ds_read_b128 v[114:117], v114 offset:3072
	ds_read_b128 v[150:153], v162
	ds_read_b128 v[154:157], v162 offset:1024
	ds_read_b128 v[158:161], v162 offset:2048
	ds_read_b128 v[162:165], v162 offset:3072
	s_add_u32 s26, s26, s42
	s_addc_u32 s27, s27, 0
	s_mov_b32 m0, s59
	ds_read_b128 v[166:169], v236 offset:32768
	ds_read_b128 v[170:173], v236 offset:33792
	ds_read_b128 v[174:177], v236 offset:34816
	ds_read_b128 v[178:181], v236 offset:35840
	ds_read_b128 v[196:199], v236 offset:36864
	ds_read_b128 v[200:203], v236 offset:37888
	ds_read_b128 v[204:207], v236 offset:38912
	ds_read_b128 v[208:211], v236 offset:39936
	global_load_lds_dwordx4 v182, s[26:27]
	s_mov_b32 m0, s62
	s_nop 0
	global_load_lds_dwordx4 v188, s[26:27]
	s_waitcnt vmcnt(8)
	s_waitcnt lgkmcnt(0)
	s_barrier
	s_setprio 1
	v_mfma_f32_16x16x32_bf16 v[146:149], v[94:97], v[166:169], v[146:149]
	v_mfma_f32_16x16x32_bf16 v[142:145], v[110:113], v[166:169], v[142:145]
	v_mfma_f32_16x16x32_bf16 v[130:133], v[94:97], v[174:177], v[130:133]
	v_mfma_f32_16x16x32_bf16 v[126:129], v[110:113], v[174:177], v[126:129]
	v_mfma_f32_16x16x32_bf16 v[106:109], v[94:97], v[196:199], v[106:109]
	v_mfma_f32_16x16x32_bf16 v[98:101], v[110:113], v[196:199], v[98:101]
	v_mfma_f32_16x16x32_bf16 v[82:85], v[94:97], v[204:207], v[82:85]
	v_mfma_f32_16x16x32_bf16 v[78:81], v[110:113], v[204:207], v[78:81]
	v_mfma_f32_16x16x32_bf16 v[146:149], v[102:105], v[170:173], v[146:149]
	v_mfma_f32_16x16x32_bf16 v[142:145], v[114:117], v[170:173], v[142:145]
	v_mfma_f32_16x16x32_bf16 v[130:133], v[102:105], v[178:181], v[130:133]
	v_mfma_f32_16x16x32_bf16 v[126:129], v[114:117], v[178:181], v[126:129]
	v_mfma_f32_16x16x32_bf16 v[106:109], v[102:105], v[200:203], v[106:109]
	v_mfma_f32_16x16x32_bf16 v[98:101], v[114:117], v[200:203], v[98:101]
	v_mfma_f32_16x16x32_bf16 v[82:85], v[102:105], v[208:211], v[82:85]
	v_mfma_f32_16x16x32_bf16 v[78:81], v[114:117], v[208:211], v[78:81]
	v_mfma_f32_16x16x32_bf16 v[138:141], v[150:153], v[166:169], v[138:141]
	v_mfma_f32_16x16x32_bf16 v[134:137], v[158:161], v[166:169], v[134:137]
	v_mfma_f32_16x16x32_bf16 v[122:125], v[150:153], v[174:177], v[122:125]
	v_mfma_f32_16x16x32_bf16 v[118:121], v[158:161], v[174:177], v[118:121]
	v_mfma_f32_16x16x32_bf16 v[90:93], v[150:153], v[196:199], v[90:93]
	v_mfma_f32_16x16x32_bf16 v[86:89], v[158:161], v[196:199], v[86:89]
	v_mfma_f32_16x16x32_bf16 v[74:77], v[150:153], v[204:207], v[74:77]
	v_mfma_f32_16x16x32_bf16 v[70:73], v[158:161], v[204:207], v[70:73]
	v_mfma_f32_16x16x32_bf16 v[138:141], v[154:157], v[170:173], v[138:141]
	v_mfma_f32_16x16x32_bf16 v[134:137], v[162:165], v[170:173], v[134:137]
	v_mfma_f32_16x16x32_bf16 v[122:125], v[154:157], v[178:181], v[122:125]
	v_mfma_f32_16x16x32_bf16 v[118:121], v[162:165], v[178:181], v[118:121]
	v_mfma_f32_16x16x32_bf16 v[90:93], v[154:157], v[200:203], v[90:93]
	v_mfma_f32_16x16x32_bf16 v[86:89], v[162:165], v[200:203], v[86:89]
	v_mfma_f32_16x16x32_bf16 v[74:77], v[154:157], v[208:211], v[74:77]
	v_mfma_f32_16x16x32_bf16 v[70:73], v[162:165], v[208:211], v[70:73]
	s_setprio 0
	s_barrier
	s_add_i32 s32, s45, s54
	s_mov_b32 m0, s32
	ds_read_b128 v[166:169], v236 offset:49152
	ds_read_b128 v[170:173], v236 offset:50176
	ds_read_b128 v[174:177], v236 offset:51200
	ds_read_b128 v[178:181], v236 offset:52224
	ds_read_b128 v[196:199], v236 offset:53248
	ds_read_b128 v[200:203], v236 offset:54272
	ds_read_b128 v[204:207], v236 offset:55296
	ds_read_b128 v[208:211], v236 offset:56320
	global_load_lds_dwordx4 v0, s[100:101]
	s_add_i32 m0, s32, 0x2000
	s_add_i32 s32, s54, 0x1c000
	global_load_lds_dwordx4 v190, s[100:101]
	s_add_u32 s70, s70, 0x80
	s_addc_u32 s71, s71, 0
	s_mov_b32 m0, s32
	s_add_i32 s32, s32, 0x2000
	global_load_lds_dwordx4 v0, s[70:71]
	s_mov_b32 m0, s32
	s_sub_u32 s26, s26, s42
	s_subb_u32 s27, s27, 0
	global_load_lds_dwordx4 v190, s[70:71]
	s_add_u32 s26, s26, 0x80
	s_addc_u32 s27, s27, 0
	s_mov_b32 m0, s63
	s_nop 0
	global_load_lds_dwordx4 v182, s[26:27]
	s_mov_b32 m0, s66
	s_nop 0
	global_load_lds_dwordx4 v188, s[26:27]
	s_waitcnt vmcnt(8)
	s_waitcnt lgkmcnt(0)
	s_barrier
	s_setprio 1
	v_mfma_f32_16x16x32_bf16 v[66:69], v[94:97], v[166:169], v[66:69]
	v_mfma_f32_16x16x32_bf16 v[62:65], v[110:113], v[166:169], v[62:65]
	v_mfma_f32_16x16x32_bf16 v[50:53], v[94:97], v[174:177], v[50:53]
	v_mfma_f32_16x16x32_bf16 v[46:49], v[110:113], v[174:177], v[46:49]
	v_mfma_f32_16x16x32_bf16 v[34:37], v[94:97], v[196:199], v[34:37]
	v_mfma_f32_16x16x32_bf16 v[30:33], v[110:113], v[196:199], v[30:33]
	v_mfma_f32_16x16x32_bf16 v[18:21], v[94:97], v[204:207], v[18:21]
	v_mfma_f32_16x16x32_bf16 v[14:17], v[110:113], v[204:207], v[14:17]
	v_mfma_f32_16x16x32_bf16 v[66:69], v[102:105], v[170:173], v[66:69]
	v_mfma_f32_16x16x32_bf16 v[62:65], v[114:117], v[170:173], v[62:65]
	v_mfma_f32_16x16x32_bf16 v[50:53], v[102:105], v[178:181], v[50:53]
	v_mfma_f32_16x16x32_bf16 v[46:49], v[114:117], v[178:181], v[46:49]
	v_mfma_f32_16x16x32_bf16 v[34:37], v[102:105], v[200:203], v[34:37]
	v_mfma_f32_16x16x32_bf16 v[30:33], v[114:117], v[200:203], v[30:33]
	v_mfma_f32_16x16x32_bf16 v[18:21], v[102:105], v[208:211], v[18:21]
	v_mfma_f32_16x16x32_bf16 v[14:17], v[114:117], v[208:211], v[14:17]
	v_mfma_f32_16x16x32_bf16 v[58:61], v[150:153], v[166:169], v[58:61]
	v_mfma_f32_16x16x32_bf16 v[54:57], v[158:161], v[166:169], v[54:57]
	v_mfma_f32_16x16x32_bf16 v[42:45], v[150:153], v[174:177], v[42:45]
	v_mfma_f32_16x16x32_bf16 v[38:41], v[158:161], v[174:177], v[38:41]
	v_mfma_f32_16x16x32_bf16 v[26:29], v[150:153], v[196:199], v[26:29]
	v_mfma_f32_16x16x32_bf16 v[22:25], v[158:161], v[196:199], v[22:25]
	v_mfma_f32_16x16x32_bf16 v[10:13], v[150:153], v[204:207], v[10:13]
	v_mfma_f32_16x16x32_bf16 v[6:9], v[158:161], v[204:207], v[6:9]
	v_mfma_f32_16x16x32_bf16 v[58:61], v[154:157], v[170:173], v[58:61]
	v_mfma_f32_16x16x32_bf16 v[54:57], v[162:165], v[170:173], v[54:57]
	v_mfma_f32_16x16x32_bf16 v[42:45], v[154:157], v[178:181], v[42:45]
	v_mfma_f32_16x16x32_bf16 v[38:41], v[162:165], v[178:181], v[38:41]
	v_mfma_f32_16x16x32_bf16 v[26:29], v[154:157], v[200:203], v[26:29]
	v_mfma_f32_16x16x32_bf16 v[22:25], v[162:165], v[200:203], v[22:25]
	v_mfma_f32_16x16x32_bf16 v[10:13], v[154:157], v[208:211], v[10:13]
	v_mfma_f32_16x16x32_bf16 v[6:9], v[162:165], v[208:211], v[6:9]
	s_setprio 0
	s_barrier
	s_add_u32 s10, s10, 0x100
	s_addc_u32 s11, s11, 0
	s_add_u32 s30, s30, 0x100
	s_addc_u32 s31, s31, 0
	s_cmp_ge_u32 s44, s67
	s_mov_b32 s26, s44
	s_cbranch_scc0 .LBB0_1065
	s_and_b64 vcc, exec, s[20:21]
	s_cbranch_vccnz .LBB0_1096
	s_mov_b64 s[30:31], 0
	s_andn2_b64 vcc, exec, s[22:23]
	s_mov_b64 s[26:27], 0
	s_cbranch_vccz .LBB0_1097
